# prologue x->bf16: 4 row-quarter loads in flight per row (counted waits), wave sum via permlane swaps + DPP (same add order)
# baseline (speedup 1.0000x reference)
.LBB0_255:
	s_waitcnt lgkmcnt(0)
	global_load_dwordx4 v[16:19], v[8:9], off
	global_load_dwordx4 v[24:27], v[8:9], off offset:1024
	global_load_dwordx4 v[28:31], v[8:9], off offset:2048
	global_load_dwordx4 v[32:35], v[8:9], off offset:3072
	s_waitcnt vmcnt(3)
	v_mul_f32_e32 v2, v17, v17
	v_fmac_f32_e32 v2, v16, v16
	v_mul_f32_e32 v20, v19, v19
	v_fmac_f32_e32 v20, v18, v18
	v_cvt_pk_bf16_f32 v36, v16, v17
	v_cvt_pk_bf16_f32 v37, v18, v19
	v_add_f32_e32 v2, v2, v20
	global_store_dwordx2 v[6:7], v[36:37], off offset:-1024
	s_waitcnt vmcnt(3)
	v_mul_f32_e32 v20, v25, v25
	v_fmac_f32_e32 v20, v24, v24
	v_mul_f32_e32 v21, v27, v27
	v_fmac_f32_e32 v21, v26, v26
	v_cvt_pk_bf16_f32 v38, v24, v25
	v_cvt_pk_bf16_f32 v39, v26, v27
	v_add_f32_e32 v20, v20, v21
	v_add_f32_e32 v2, v2, v20
	global_store_dwordx2 v[6:7], v[38:39], off offset:-512
	s_waitcnt vmcnt(3)
	v_mul_f32_e32 v20, v29, v29
	v_fmac_f32_e32 v20, v28, v28
	v_mul_f32_e32 v21, v31, v31
	v_fmac_f32_e32 v21, v30, v30
	v_cvt_pk_bf16_f32 v40, v28, v29
	v_cvt_pk_bf16_f32 v41, v30, v31
	v_add_f32_e32 v20, v20, v21
	v_add_f32_e32 v2, v2, v20
	global_store_dwordx2 v[6:7], v[40:41], off
	s_waitcnt vmcnt(3)
	v_mul_f32_e32 v20, v33, v33
	v_fmac_f32_e32 v20, v32, v32
	v_mul_f32_e32 v21, v35, v35
	v_fmac_f32_e32 v21, v34, v34
	v_cvt_pk_bf16_f32 v42, v32, v33
	v_cvt_pk_bf16_f32 v43, v34, v35
	v_add_f32_e32 v20, v20, v21
	v_add_f32_e32 v2, v2, v20
	global_store_dwordx2 v[6:7], v[42:43], off offset:512
	v_mov_b32_e32 v16, v2
	s_nop 1
	v_permlane32_swap_b32_e32 v2, v16
	v_add_f32_e32 v2, v2, v16
	v_mov_b32_e32 v16, v2
	s_nop 1
	v_permlane16_swap_b32_e32 v2, v16
	v_add_f32_e32 v2, v2, v16
	s_nop 1
	v_add_f32_dpp v2, v2, v2 row_ror:8 row_mask:0xf bank_mask:0xf
	s_nop 1
	v_add_f32_dpp v2, v2, v2 row_ror:4 row_mask:0xf bank_mask:0xf
	s_nop 1
	v_add_f32_dpp v2, v2, v2 quad_perm:[2,3,0,1] row_mask:0xf bank_mask:0xf
	s_nop 1
	v_add_f32_dpp v2, v2, v2 quad_perm:[1,0,3,2] row_mask:0xf bank_mask:0xf
	s_and_saveexec_b64 s[4:5], vcc
	s_cbranch_execz .LBB0_254
	v_cndmask_b32_e64 v2, 0, v2, s[0:1]
	global_store_dword v[4:5], v2, off
	s_branch .LBB0_254
